# same kernel as previous version; code after the scan phase moved by 512 bytes (padding after an unconditional branch) for instruction placement
# baseline (speedup 1.0000x reference)
; DI unsigned cvtpk_n(float lo, float hi) { f32x2 v = {lo, hi}; bf16x2n b = __builtin_convertvector(v, bf16x2n); return __builtin_bit_cast(unsigned, b); }
; DI void scan_ld(ScanStep& t, const float* rec, const char* zimg, int fragoff, bool isaq, int h, int m, int vrow) {
;     const char* fp = isaq ? (const char*)(rec + fragoff) + h * 16 : zimg + h * 16;
; #pragma unroll
;     for (int q = 0; q < 4; ++q) t.f[q] = *(const bf16x8*)(fp + q * 32);
; DI void phase_scan(const bf16_t* R, const bf16_t* Kk, const bf16_t* V, const __half* DEC, const bf16_t* AA, const float* INV, const float* kkp, const float* kap,
;                    bf16_t* MIX, bf16_t* YB, char* lds) {
;     ...
;                 const float* cur = bufA + cgrp * 12288 + (c & 1) * 6144; float* yb = ybufA + cgrp * 2048 + (c & 1) * 1024;
;                 ScanStep t; scan_ld(t, cur, zimg, fragoff, isaq, h, m, vrow);
; #pragma unroll 2
;                 for (int st = 0; st < 16; ++st) {
;                     f32x16 d0 = __builtin_amdgcn_mfma_f32_32x32x16_bf16(t.f[0], pack_acc(acc0, 0), zero16, 0, 0, 0);
;                     d0 = __builtin_amdgcn_mfma_f32_32x32x16_bf16(t.f[1], pack_acc(acc0, 1), d0, 0, 0, 0);
;                     d0 = __builtin_amdgcn_mfma_f32_32x32x16_bf16(t.f[2], pack_acc(acc1, 0), d0, 0, 0, 0);
;                     d0 = __builtin_amdgcn_mfma_f32_32x32x16_bf16(t.f[3], pack_acc(acc1, 1), d0, 0, 0, 0);
;                     __builtin_amdgcn_sched_barrier(0);
;                     ScanStep n; scan_ld(n, cur + (st + 1) * SREC, zimg, fragoff, isaq, h, m, vrow);
;                     __builtin_amdgcn_sched_barrier(0);
;                     const float sa = d0[0], z = d0[1];
;                     yb[st * 64 + vrow] = z + sa * ((t.brp[0] + t.brp[1]) + (t.brp[2] + t.brp[3])) + t.v * ((t.krp[0] + t.krp[1]) + (t.krp[2] + t.krp[3]));
;                     const unsigned hz = h ? 0u : 0xffffffffu;
;                     const u32x4 ua0 = {cvtpk_n(t.b0, t.k0) & hz, 0u, 0u, 0u}, ua1 = {cvtpk_n(t.b1, t.k1) & hz, 0u, 0u, 0u}, ub = {cvtpk_n(sa, t.v) & hz, 0u, 0u, 0u};
;                     acc0 = __builtin_amdgcn_mfma_f32_32x32x16_bf16(__builtin_bit_cast(bf16x8, ua0), __builtin_bit_cast(bf16x8, ub), acc0, 0, 0, 0);
;                     acc1 = __builtin_amdgcn_mfma_f32_32x32x16_bf16(__builtin_bit_cast(bf16x8, ua1), __builtin_bit_cast(bf16x8, ub), acc1, 0, 0, 0);
;                     t = n;
.LBB0_2301:
	s_andn2_saveexec_b64 s[20:21], s[20:21]
	s_cbranch_execz .LBB0_2281
	s_and_b32 s14, s12, 1
	s_mulk_i32 s14, 0x6000
	v_cndmask_b32_e64 v0, 0, 1, s[88:89]
	v_add_u32_e32 v170, s14, v132
	v_mul_lo_u32 v2, v0, s73
	v_lshl_add_u32 v169, v0, 12, v164
	v_add_u32_e32 v191, 0x18000, v169
	v_add_u32_e32 v168, v163, v2
	v_cndmask_b32_e64 v188, v134, v168, s[40:41]
	v_lshl_add_u32 v189, v122, 2, v170
	v_add_u32_e32 v189, 0x100, v189
	v_mov_b32_e32 v0, s24
	v_bfi_b32 v189, v135, v189, v0
	v_lshl_add_u32 v190, v123, 2, v170
	v_add_u32_e32 v190, 0x300, v190
	v_mov_b32_e32 v81, 0
	v_mov_b32_e32 v82, 0
	v_mov_b32_e32 v83, 0
	v_mov_b32_e32 v85, 0
	v_mov_b32_e32 v86, 0
	v_mov_b32_e32 v87, 0
	s_mov_b64 exec, s[40:41]
	ds_read_b128 v[64:67], v188
	ds_read_b128 v[68:71], v188 offset:32
	ds_read_b128 v[72:75], v188 offset:64
	ds_read_b128 v[76:79], v188 offset:96
	s_mov_b64 exec, -1
	ds_read_b32 v224, v189
	ds_read_b32 v228, v189 offset:128
	ds_read_b32 v108, v190
	ds_read_b128 v[4:7], v170 offset:1024
	ds_read_b128 v[8:11], v170 offset:1040
	s_waitcnt lgkmcnt(0)
	s_waitcnt lgkmcnt(1)
	s_mov_b64 exec, s[40:41]
	ds_read_b128 v[192:195], v188 offset:1056
	ds_read_b128 v[196:199], v188 offset:1088
	ds_read_b128 v[200:203], v188 offset:1120
	ds_read_b128 v[204:207], v188 offset:1152
	s_mov_b64 exec, -1
	ds_read_b32 v80, v189 offset:1056
	ds_read_b32 v84, v189 offset:1184
	ds_read_b32 v114, v190 offset:1056
	v_cvt_pk_bf16_f32 v216, v16, v17
	v_cvt_pk_bf16_f32 v217, v18, v19
	v_cvt_pk_bf16_f32 v218, v20, v21
	v_cvt_pk_bf16_f32 v219, v22, v23
	ds_read_b128 v[208:211], v170 offset:2080
	ds_read_b128 v[212:215], v170 offset:2096
	v_mfma_f32_32x32x16_bf16 v[48:63], v[64:67], v[216:219], 0
	v_cvt_pk_bf16_f32 v220, v24, v25
	v_cvt_pk_bf16_f32 v221, v26, v27
	v_cvt_pk_bf16_f32 v222, v28, v29
	v_cvt_pk_bf16_f32 v223, v30, v31
	v_add_f32_e32 v2, v4, v5
	v_add_f32_e32 v3, v8, v9
	v_mfma_f32_32x32x16_bf16 v[48:63], v[68:71], v[220:223], v[48:63]
	v_cvt_pk_bf16_f32 v216, v32, v33
	v_cvt_pk_bf16_f32 v217, v34, v35
	v_cvt_pk_bf16_f32 v218, v36, v37
	v_cvt_pk_bf16_f32 v219, v38, v39
	v_add_f32_e32 v0, v6, v7
	v_add_f32_e32 v14, v10, v11
	v_mfma_f32_32x32x16_bf16 v[48:63], v[72:75], v[216:219], v[48:63]
	v_cvt_pk_bf16_f32 v220, v40, v41
	v_cvt_pk_bf16_f32 v221, v42, v43
	v_cvt_pk_bf16_f32 v222, v44, v45
	v_cvt_pk_bf16_f32 v223, v46, v47
	v_add_f32_e32 v2, v2, v0
	v_add_f32_e32 v3, v3, v14
	v_mfma_f32_32x32x16_bf16 v[48:63], v[76:79], v[220:223], v[48:63]
	s_nop 11
	v_cvt_pk_bf16_f32 v232, v48, v108
	v_fma_f32 v13, v48, v2, v49
	v_fma_f32 v13, v108, v3, v13
	v_mfma_f32_32x32x16_bf16 v[16:31], v[224:227], v[232:235], v[16:31]
	v_mfma_f32_32x32x16_bf16 v[32:47], v[228:231], v[232:235], v[32:47]
	ds_write_b32 v191, v13 offset:0
	s_waitcnt lgkmcnt(1)
	s_mov_b64 exec, s[40:41]
	ds_read_b128 v[64:67], v188 offset:2112
	ds_read_b128 v[68:71], v188 offset:2144
	ds_read_b128 v[72:75], v188 offset:2176
	ds_read_b128 v[76:79], v188 offset:2208
	s_mov_b64 exec, -1
	ds_read_b32 v224, v189 offset:2112
	ds_read_b32 v228, v189 offset:2240
	ds_read_b32 v108, v190 offset:2112
	v_cvt_pk_bf16_f32 v216, v16, v17
	v_cvt_pk_bf16_f32 v217, v18, v19
	v_cvt_pk_bf16_f32 v218, v20, v21
	v_cvt_pk_bf16_f32 v219, v22, v23
	ds_read_b128 v[4:7], v170 offset:3136
	ds_read_b128 v[8:11], v170 offset:3152
	v_mfma_f32_32x32x16_bf16 v[48:63], v[192:195], v[216:219], 0
	v_cvt_pk_bf16_f32 v220, v24, v25
	v_cvt_pk_bf16_f32 v221, v26, v27
	v_cvt_pk_bf16_f32 v222, v28, v29
	v_cvt_pk_bf16_f32 v223, v30, v31
	v_add_f32_e32 v2, v208, v209
	v_add_f32_e32 v3, v212, v213
	v_mfma_f32_32x32x16_bf16 v[48:63], v[196:199], v[220:223], v[48:63]
	v_cvt_pk_bf16_f32 v216, v32, v33
	v_cvt_pk_bf16_f32 v217, v34, v35
	v_cvt_pk_bf16_f32 v218, v36, v37
	v_cvt_pk_bf16_f32 v219, v38, v39
	v_add_f32_e32 v0, v210, v211
	v_add_f32_e32 v14, v214, v215
	v_mfma_f32_32x32x16_bf16 v[48:63], v[200:203], v[216:219], v[48:63]
	v_cvt_pk_bf16_f32 v220, v40, v41
	v_cvt_pk_bf16_f32 v221, v42, v43
	v_cvt_pk_bf16_f32 v222, v44, v45
	v_cvt_pk_bf16_f32 v223, v46, v47
	v_add_f32_e32 v2, v2, v0
	v_add_f32_e32 v3, v3, v14
	v_mfma_f32_32x32x16_bf16 v[48:63], v[204:207], v[220:223], v[48:63]
	s_nop 11
	v_cvt_pk_bf16_f32 v232, v48, v114
	v_fma_f32 v13, v48, v2, v49
	v_fma_f32 v13, v114, v3, v13
	v_mfma_f32_32x32x16_bf16 v[16:31], v[80:83], v[232:235], v[16:31]
	v_mfma_f32_32x32x16_bf16 v[32:47], v[84:87], v[232:235], v[32:47]
	ds_write_b32 v191, v13 offset:256
	s_waitcnt lgkmcnt(1)
	s_mov_b64 exec, s[40:41]
	ds_read_b128 v[192:195], v188 offset:3168
	ds_read_b128 v[196:199], v188 offset:3200
	ds_read_b128 v[200:203], v188 offset:3232
	ds_read_b128 v[204:207], v188 offset:3264
	s_mov_b64 exec, -1
	ds_read_b32 v80, v189 offset:3168
	ds_read_b32 v84, v189 offset:3296
	ds_read_b32 v114, v190 offset:3168
	v_cvt_pk_bf16_f32 v216, v16, v17
	v_cvt_pk_bf16_f32 v217, v18, v19
	v_cvt_pk_bf16_f32 v218, v20, v21
	v_cvt_pk_bf16_f32 v219, v22, v23
	ds_read_b128 v[208:211], v170 offset:4192
	ds_read_b128 v[212:215], v170 offset:4208
	v_mfma_f32_32x32x16_bf16 v[48:63], v[64:67], v[216:219], 0
	v_cvt_pk_bf16_f32 v220, v24, v25
	v_cvt_pk_bf16_f32 v221, v26, v27
	v_cvt_pk_bf16_f32 v222, v28, v29
	v_cvt_pk_bf16_f32 v223, v30, v31
	v_add_f32_e32 v2, v4, v5
	v_add_f32_e32 v3, v8, v9
	v_mfma_f32_32x32x16_bf16 v[48:63], v[68:71], v[220:223], v[48:63]
	v_cvt_pk_bf16_f32 v216, v32, v33
	v_cvt_pk_bf16_f32 v217, v34, v35
	v_cvt_pk_bf16_f32 v218, v36, v37
	v_cvt_pk_bf16_f32 v219, v38, v39
	v_add_f32_e32 v0, v6, v7
	v_add_f32_e32 v14, v10, v11
	v_mfma_f32_32x32x16_bf16 v[48:63], v[72:75], v[216:219], v[48:63]
	v_cvt_pk_bf16_f32 v220, v40, v41
	v_cvt_pk_bf16_f32 v221, v42, v43
	v_cvt_pk_bf16_f32 v222, v44, v45
	v_cvt_pk_bf16_f32 v223, v46, v47
	v_add_f32_e32 v2, v2, v0
	v_add_f32_e32 v3, v3, v14
	v_mfma_f32_32x32x16_bf16 v[48:63], v[76:79], v[220:223], v[48:63]
	s_nop 11
	v_cvt_pk_bf16_f32 v232, v48, v108
	v_fma_f32 v13, v48, v2, v49
	v_fma_f32 v13, v108, v3, v13
	v_mfma_f32_32x32x16_bf16 v[16:31], v[224:227], v[232:235], v[16:31]
	v_mfma_f32_32x32x16_bf16 v[32:47], v[228:231], v[232:235], v[32:47]
	ds_write_b32 v191, v13 offset:512
	s_waitcnt lgkmcnt(1)
; DI unsigned cvtpk_n(float lo, float hi) { f32x2 v = {lo, hi}; bf16x2n b = __builtin_convertvector(v, bf16x2n); return __builtin_bit_cast(unsigned, b); }
; DI void scan_ld(ScanStep& t, const float* rec, const char* zimg, int fragoff, bool isaq, int h, int m, int vrow) {
;     const char* fp = isaq ? (const char*)(rec + fragoff) + h * 16 : zimg + h * 16;
; #pragma unroll
;     for (int q = 0; q < 4; ++q) t.f[q] = *(const bf16x8*)(fp + q * 32);
;     t.b0 = rec[64 + m]; t.k0 = rec[128 + m]; t.b1 = rec[96 + m]; t.k1 = rec[160 + m]; t.v = rec[192 + vrow]; t.brp = *(const f32x4*)(rec + 256); t.krp = *(const f32x4*)(rec + 260);
; }
; DI void phase_scan(const bf16_t* R, const bf16_t* Kk, const bf16_t* V, const __half* DEC, const bf16_t* AA, const float* INV, const float* kkp, const float* kap,
;                    bf16_t* MIX, bf16_t* YB, char* lds) {
;     ...
;                 for (int st = 0; st < 16; ++st) {
;                     f32x16 d0 = __builtin_amdgcn_mfma_f32_32x32x16_bf16(t.f[0], pack_acc(acc0, 0), zero16, 0, 0, 0);
;                     d0 = __builtin_amdgcn_mfma_f32_32x32x16_bf16(t.f[1], pack_acc(acc0, 1), d0, 0, 0, 0);
;                     d0 = __builtin_amdgcn_mfma_f32_32x32x16_bf16(t.f[2], pack_acc(acc1, 0), d0, 0, 0, 0);
;                     d0 = __builtin_amdgcn_mfma_f32_32x32x16_bf16(t.f[3], pack_acc(acc1, 1), d0, 0, 0, 0);
;                     __builtin_amdgcn_sched_barrier(0);
;                     ScanStep n; scan_ld(n, cur + (st + 1) * SREC, zimg, fragoff, isaq, h, m, vrow);
;                     __builtin_amdgcn_sched_barrier(0);
;                     const float sa = d0[0], z = d0[1];
;                     yb[st * 64 + vrow] = z + sa * ((t.brp[0] + t.brp[1]) + (t.brp[2] + t.brp[3])) + t.v * ((t.krp[0] + t.krp[1]) + (t.krp[2] + t.krp[3]));
;                     const unsigned hz = h ? 0u : 0xffffffffu;
;                     const u32x4 ua0 = {cvtpk_n(t.b0, t.k0) & hz, 0u, 0u, 0u}, ua1 = {cvtpk_n(t.b1, t.k1) & hz, 0u, 0u, 0u}, ub = {cvtpk_n(sa, t.v) & hz, 0u, 0u, 0u};
;                     acc0 = __builtin_amdgcn_mfma_f32_32x32x16_bf16(__builtin_bit_cast(bf16x8, ua0), __builtin_bit_cast(bf16x8, ub), acc0, 0, 0, 0);
;                     acc1 = __builtin_amdgcn_mfma_f32_32x32x16_bf16(__builtin_bit_cast(bf16x8, ua1), __builtin_bit_cast(bf16x8, ub), acc1, 0, 0, 0);
;                     t = n;
	s_mov_b64 exec, s[40:41]
	ds_read_b128 v[64:67], v188 offset:4224
	ds_read_b128 v[68:71], v188 offset:4256
	ds_read_b128 v[72:75], v188 offset:4288
	ds_read_b128 v[76:79], v188 offset:4320
	s_mov_b64 exec, -1
	ds_read_b32 v224, v189 offset:4224
	ds_read_b32 v228, v189 offset:4352
	ds_read_b32 v108, v190 offset:4224
	v_cvt_pk_bf16_f32 v216, v16, v17
	v_cvt_pk_bf16_f32 v217, v18, v19
	v_cvt_pk_bf16_f32 v218, v20, v21
	v_cvt_pk_bf16_f32 v219, v22, v23
	ds_read_b128 v[4:7], v170 offset:5248
	ds_read_b128 v[8:11], v170 offset:5264
	v_mfma_f32_32x32x16_bf16 v[48:63], v[192:195], v[216:219], 0
	v_cvt_pk_bf16_f32 v220, v24, v25
	v_cvt_pk_bf16_f32 v221, v26, v27
	v_cvt_pk_bf16_f32 v222, v28, v29
	v_cvt_pk_bf16_f32 v223, v30, v31
	v_add_f32_e32 v2, v208, v209
	v_add_f32_e32 v3, v212, v213
	v_mfma_f32_32x32x16_bf16 v[48:63], v[196:199], v[220:223], v[48:63]
	v_cvt_pk_bf16_f32 v216, v32, v33
	v_cvt_pk_bf16_f32 v217, v34, v35
	v_cvt_pk_bf16_f32 v218, v36, v37
	v_cvt_pk_bf16_f32 v219, v38, v39
	v_add_f32_e32 v0, v210, v211
	v_add_f32_e32 v14, v214, v215
	v_mfma_f32_32x32x16_bf16 v[48:63], v[200:203], v[216:219], v[48:63]
	v_cvt_pk_bf16_f32 v220, v40, v41
	v_cvt_pk_bf16_f32 v221, v42, v43
	v_cvt_pk_bf16_f32 v222, v44, v45
	v_cvt_pk_bf16_f32 v223, v46, v47
	v_add_f32_e32 v2, v2, v0
	v_add_f32_e32 v3, v3, v14
	v_mfma_f32_32x32x16_bf16 v[48:63], v[204:207], v[220:223], v[48:63]
	s_nop 11
	v_cvt_pk_bf16_f32 v232, v48, v114
	v_fma_f32 v13, v48, v2, v49
	v_fma_f32 v13, v114, v3, v13
	v_mfma_f32_32x32x16_bf16 v[16:31], v[80:83], v[232:235], v[16:31]
	v_mfma_f32_32x32x16_bf16 v[32:47], v[84:87], v[232:235], v[32:47]
	ds_write_b32 v191, v13 offset:768
	s_waitcnt lgkmcnt(1)
	s_mov_b64 exec, s[40:41]
	ds_read_b128 v[192:195], v188 offset:5280
	ds_read_b128 v[196:199], v188 offset:5312
	ds_read_b128 v[200:203], v188 offset:5344
	ds_read_b128 v[204:207], v188 offset:5376
	s_mov_b64 exec, -1
	ds_read_b32 v80, v189 offset:5280
	ds_read_b32 v84, v189 offset:5408
	ds_read_b32 v114, v190 offset:5280
	v_cvt_pk_bf16_f32 v216, v16, v17
	v_cvt_pk_bf16_f32 v217, v18, v19
	v_cvt_pk_bf16_f32 v218, v20, v21
	v_cvt_pk_bf16_f32 v219, v22, v23
	ds_read_b128 v[208:211], v170 offset:6304
	ds_read_b128 v[212:215], v170 offset:6320
	v_mfma_f32_32x32x16_bf16 v[48:63], v[64:67], v[216:219], 0
	v_cvt_pk_bf16_f32 v220, v24, v25
	v_cvt_pk_bf16_f32 v221, v26, v27
	v_cvt_pk_bf16_f32 v222, v28, v29
	v_cvt_pk_bf16_f32 v223, v30, v31
	v_add_f32_e32 v2, v4, v5
	v_add_f32_e32 v3, v8, v9
	v_mfma_f32_32x32x16_bf16 v[48:63], v[68:71], v[220:223], v[48:63]
	v_cvt_pk_bf16_f32 v216, v32, v33
	v_cvt_pk_bf16_f32 v217, v34, v35
	v_cvt_pk_bf16_f32 v218, v36, v37
	v_cvt_pk_bf16_f32 v219, v38, v39
	v_add_f32_e32 v0, v6, v7
	v_add_f32_e32 v14, v10, v11
	v_mfma_f32_32x32x16_bf16 v[48:63], v[72:75], v[216:219], v[48:63]
	v_cvt_pk_bf16_f32 v220, v40, v41
	v_cvt_pk_bf16_f32 v221, v42, v43
	v_cvt_pk_bf16_f32 v222, v44, v45
	v_cvt_pk_bf16_f32 v223, v46, v47
	v_add_f32_e32 v2, v2, v0
	v_add_f32_e32 v3, v3, v14
	v_mfma_f32_32x32x16_bf16 v[48:63], v[76:79], v[220:223], v[48:63]
	s_nop 11
	v_cvt_pk_bf16_f32 v232, v48, v108
	v_fma_f32 v13, v48, v2, v49
	v_fma_f32 v13, v108, v3, v13
	v_mfma_f32_32x32x16_bf16 v[16:31], v[224:227], v[232:235], v[16:31]
	v_mfma_f32_32x32x16_bf16 v[32:47], v[228:231], v[232:235], v[32:47]
	ds_write_b32 v191, v13 offset:1024
	s_waitcnt lgkmcnt(1)
	s_mov_b64 exec, s[40:41]
	ds_read_b128 v[64:67], v188 offset:6336
	ds_read_b128 v[68:71], v188 offset:6368
	ds_read_b128 v[72:75], v188 offset:6400
	ds_read_b128 v[76:79], v188 offset:6432
	s_mov_b64 exec, -1
	ds_read_b32 v224, v189 offset:6336
	ds_read_b32 v228, v189 offset:6464
	ds_read_b32 v108, v190 offset:6336
	v_cvt_pk_bf16_f32 v216, v16, v17
	v_cvt_pk_bf16_f32 v217, v18, v19
	v_cvt_pk_bf16_f32 v218, v20, v21
	v_cvt_pk_bf16_f32 v219, v22, v23
	ds_read_b128 v[4:7], v170 offset:7360
	ds_read_b128 v[8:11], v170 offset:7376
	v_mfma_f32_32x32x16_bf16 v[48:63], v[192:195], v[216:219], 0
	v_cvt_pk_bf16_f32 v220, v24, v25
	v_cvt_pk_bf16_f32 v221, v26, v27
	v_cvt_pk_bf16_f32 v222, v28, v29
	v_cvt_pk_bf16_f32 v223, v30, v31
	v_add_f32_e32 v2, v208, v209
	v_add_f32_e32 v3, v212, v213
	v_mfma_f32_32x32x16_bf16 v[48:63], v[196:199], v[220:223], v[48:63]
	v_cvt_pk_bf16_f32 v216, v32, v33
	v_cvt_pk_bf16_f32 v217, v34, v35
	v_cvt_pk_bf16_f32 v218, v36, v37
	v_cvt_pk_bf16_f32 v219, v38, v39
	v_add_f32_e32 v0, v210, v211
	v_add_f32_e32 v14, v214, v215
	v_mfma_f32_32x32x16_bf16 v[48:63], v[200:203], v[216:219], v[48:63]
	v_cvt_pk_bf16_f32 v220, v40, v41
	v_cvt_pk_bf16_f32 v221, v42, v43
	v_cvt_pk_bf16_f32 v222, v44, v45
	v_cvt_pk_bf16_f32 v223, v46, v47
	v_add_f32_e32 v2, v2, v0
	v_add_f32_e32 v3, v3, v14
	v_mfma_f32_32x32x16_bf16 v[48:63], v[204:207], v[220:223], v[48:63]
	s_nop 11
	v_cvt_pk_bf16_f32 v232, v48, v114
	v_fma_f32 v13, v48, v2, v49
	v_fma_f32 v13, v114, v3, v13
	v_mfma_f32_32x32x16_bf16 v[16:31], v[80:83], v[232:235], v[16:31]
	v_mfma_f32_32x32x16_bf16 v[32:47], v[84:87], v[232:235], v[32:47]
	ds_write_b32 v191, v13 offset:1280
	s_waitcnt lgkmcnt(1)
; DI unsigned cvtpk_n(float lo, float hi) { f32x2 v = {lo, hi}; bf16x2n b = __builtin_convertvector(v, bf16x2n); return __builtin_bit_cast(unsigned, b); }
; DI void scan_ld(ScanStep& t, const float* rec, const char* zimg, int fragoff, bool isaq, int h, int m, int vrow) {
;     const char* fp = isaq ? (const char*)(rec + fragoff) + h * 16 : zimg + h * 16;
; #pragma unroll
;     for (int q = 0; q < 4; ++q) t.f[q] = *(const bf16x8*)(fp + q * 32);
;     t.b0 = rec[64 + m]; t.k0 = rec[128 + m]; t.b1 = rec[96 + m]; t.k1 = rec[160 + m]; t.v = rec[192 + vrow]; t.brp = *(const f32x4*)(rec + 256); t.krp = *(const f32x4*)(rec + 260);
; }
; DI void phase_scan(const bf16_t* R, const bf16_t* Kk, const bf16_t* V, const __half* DEC, const bf16_t* AA, const float* INV, const float* kkp, const float* kap,
;                    bf16_t* MIX, bf16_t* YB, char* lds) {
;     ...
;                 for (int st = 0; st < 16; ++st) {
;                     f32x16 d0 = __builtin_amdgcn_mfma_f32_32x32x16_bf16(t.f[0], pack_acc(acc0, 0), zero16, 0, 0, 0);
;                     d0 = __builtin_amdgcn_mfma_f32_32x32x16_bf16(t.f[1], pack_acc(acc0, 1), d0, 0, 0, 0);
;                     d0 = __builtin_amdgcn_mfma_f32_32x32x16_bf16(t.f[2], pack_acc(acc1, 0), d0, 0, 0, 0);
;                     d0 = __builtin_amdgcn_mfma_f32_32x32x16_bf16(t.f[3], pack_acc(acc1, 1), d0, 0, 0, 0);
;                     __builtin_amdgcn_sched_barrier(0);
;                     ScanStep n; scan_ld(n, cur + (st + 1) * SREC, zimg, fragoff, isaq, h, m, vrow);
;                     __builtin_amdgcn_sched_barrier(0);
;                     const float sa = d0[0], z = d0[1];
;                     yb[st * 64 + vrow] = z + sa * ((t.brp[0] + t.brp[1]) + (t.brp[2] + t.brp[3])) + t.v * ((t.krp[0] + t.krp[1]) + (t.krp[2] + t.krp[3]));
;                     const unsigned hz = h ? 0u : 0xffffffffu;
;                     const u32x4 ua0 = {cvtpk_n(t.b0, t.k0) & hz, 0u, 0u, 0u}, ua1 = {cvtpk_n(t.b1, t.k1) & hz, 0u, 0u, 0u}, ub = {cvtpk_n(sa, t.v) & hz, 0u, 0u, 0u};
;                     acc0 = __builtin_amdgcn_mfma_f32_32x32x16_bf16(__builtin_bit_cast(bf16x8, ua0), __builtin_bit_cast(bf16x8, ub), acc0, 0, 0, 0);
;                     acc1 = __builtin_amdgcn_mfma_f32_32x32x16_bf16(__builtin_bit_cast(bf16x8, ua1), __builtin_bit_cast(bf16x8, ub), acc1, 0, 0, 0);
;                     t = n;
	s_mov_b64 exec, s[40:41]
	ds_read_b128 v[192:195], v188 offset:7392
	ds_read_b128 v[196:199], v188 offset:7424
	ds_read_b128 v[200:203], v188 offset:7456
	ds_read_b128 v[204:207], v188 offset:7488
	s_mov_b64 exec, -1
	ds_read_b32 v80, v189 offset:7392
	ds_read_b32 v84, v189 offset:7520
	ds_read_b32 v114, v190 offset:7392
	v_cvt_pk_bf16_f32 v216, v16, v17
	v_cvt_pk_bf16_f32 v217, v18, v19
	v_cvt_pk_bf16_f32 v218, v20, v21
	v_cvt_pk_bf16_f32 v219, v22, v23
	ds_read_b128 v[208:211], v170 offset:8416
	ds_read_b128 v[212:215], v170 offset:8432
	v_mfma_f32_32x32x16_bf16 v[48:63], v[64:67], v[216:219], 0
	v_cvt_pk_bf16_f32 v220, v24, v25
	v_cvt_pk_bf16_f32 v221, v26, v27
	v_cvt_pk_bf16_f32 v222, v28, v29
	v_cvt_pk_bf16_f32 v223, v30, v31
	v_add_f32_e32 v2, v4, v5
	v_add_f32_e32 v3, v8, v9
	v_mfma_f32_32x32x16_bf16 v[48:63], v[68:71], v[220:223], v[48:63]
	v_cvt_pk_bf16_f32 v216, v32, v33
	v_cvt_pk_bf16_f32 v217, v34, v35
	v_cvt_pk_bf16_f32 v218, v36, v37
	v_cvt_pk_bf16_f32 v219, v38, v39
	v_add_f32_e32 v0, v6, v7
	v_add_f32_e32 v14, v10, v11
	v_mfma_f32_32x32x16_bf16 v[48:63], v[72:75], v[216:219], v[48:63]
	v_cvt_pk_bf16_f32 v220, v40, v41
	v_cvt_pk_bf16_f32 v221, v42, v43
	v_cvt_pk_bf16_f32 v222, v44, v45
	v_cvt_pk_bf16_f32 v223, v46, v47
	v_add_f32_e32 v2, v2, v0
	v_add_f32_e32 v3, v3, v14
	v_mfma_f32_32x32x16_bf16 v[48:63], v[76:79], v[220:223], v[48:63]
	s_nop 11
	v_cvt_pk_bf16_f32 v232, v48, v108
	v_fma_f32 v13, v48, v2, v49
	v_fma_f32 v13, v108, v3, v13
	v_mfma_f32_32x32x16_bf16 v[16:31], v[224:227], v[232:235], v[16:31]
	v_mfma_f32_32x32x16_bf16 v[32:47], v[228:231], v[232:235], v[32:47]
	ds_write_b32 v191, v13 offset:1536
	s_waitcnt lgkmcnt(1)
	s_mov_b64 exec, s[40:41]
	ds_read_b128 v[64:67], v188 offset:8448
	ds_read_b128 v[68:71], v188 offset:8480
	ds_read_b128 v[72:75], v188 offset:8512
	ds_read_b128 v[76:79], v188 offset:8544
	s_mov_b64 exec, -1
	ds_read_b32 v224, v189 offset:8448
	ds_read_b32 v228, v189 offset:8576
	ds_read_b32 v108, v190 offset:8448
	v_cvt_pk_bf16_f32 v216, v16, v17
	v_cvt_pk_bf16_f32 v217, v18, v19
	v_cvt_pk_bf16_f32 v218, v20, v21
	v_cvt_pk_bf16_f32 v219, v22, v23
	ds_read_b128 v[4:7], v170 offset:9472
	ds_read_b128 v[8:11], v170 offset:9488
	v_mfma_f32_32x32x16_bf16 v[48:63], v[192:195], v[216:219], 0
	v_cvt_pk_bf16_f32 v220, v24, v25
	v_cvt_pk_bf16_f32 v221, v26, v27
	v_cvt_pk_bf16_f32 v222, v28, v29
	v_cvt_pk_bf16_f32 v223, v30, v31
	v_add_f32_e32 v2, v208, v209
	v_add_f32_e32 v3, v212, v213
	v_mfma_f32_32x32x16_bf16 v[48:63], v[196:199], v[220:223], v[48:63]
	v_cvt_pk_bf16_f32 v216, v32, v33
	v_cvt_pk_bf16_f32 v217, v34, v35
	v_cvt_pk_bf16_f32 v218, v36, v37
	v_cvt_pk_bf16_f32 v219, v38, v39
	v_add_f32_e32 v0, v210, v211
	v_add_f32_e32 v14, v214, v215
	v_mfma_f32_32x32x16_bf16 v[48:63], v[200:203], v[216:219], v[48:63]
	v_cvt_pk_bf16_f32 v220, v40, v41
	v_cvt_pk_bf16_f32 v221, v42, v43
	v_cvt_pk_bf16_f32 v222, v44, v45
	v_cvt_pk_bf16_f32 v223, v46, v47
	v_add_f32_e32 v2, v2, v0
	v_add_f32_e32 v3, v3, v14
	v_mfma_f32_32x32x16_bf16 v[48:63], v[204:207], v[220:223], v[48:63]
	s_nop 11
	v_cvt_pk_bf16_f32 v232, v48, v114
	v_fma_f32 v13, v48, v2, v49
	v_fma_f32 v13, v114, v3, v13
	v_mfma_f32_32x32x16_bf16 v[16:31], v[80:83], v[232:235], v[16:31]
	v_mfma_f32_32x32x16_bf16 v[32:47], v[84:87], v[232:235], v[32:47]
	ds_write_b32 v191, v13 offset:1792
	s_waitcnt lgkmcnt(1)
	s_mov_b64 exec, s[40:41]
	ds_read_b128 v[192:195], v188 offset:9504
	ds_read_b128 v[196:199], v188 offset:9536
	ds_read_b128 v[200:203], v188 offset:9568
	ds_read_b128 v[204:207], v188 offset:9600
	s_mov_b64 exec, -1
	ds_read_b32 v80, v189 offset:9504
	ds_read_b32 v84, v189 offset:9632
	ds_read_b32 v114, v190 offset:9504
	v_cvt_pk_bf16_f32 v216, v16, v17
	v_cvt_pk_bf16_f32 v217, v18, v19
	v_cvt_pk_bf16_f32 v218, v20, v21
	v_cvt_pk_bf16_f32 v219, v22, v23
	ds_read_b128 v[208:211], v170 offset:10528
	ds_read_b128 v[212:215], v170 offset:10544
	v_mfma_f32_32x32x16_bf16 v[48:63], v[64:67], v[216:219], 0
	v_cvt_pk_bf16_f32 v220, v24, v25
	v_cvt_pk_bf16_f32 v221, v26, v27
	v_cvt_pk_bf16_f32 v222, v28, v29
	v_cvt_pk_bf16_f32 v223, v30, v31
	v_add_f32_e32 v2, v4, v5
	v_add_f32_e32 v3, v8, v9
	v_mfma_f32_32x32x16_bf16 v[48:63], v[68:71], v[220:223], v[48:63]
	v_cvt_pk_bf16_f32 v216, v32, v33
	v_cvt_pk_bf16_f32 v217, v34, v35
	v_cvt_pk_bf16_f32 v218, v36, v37
	v_cvt_pk_bf16_f32 v219, v38, v39
	v_add_f32_e32 v0, v6, v7
	v_add_f32_e32 v14, v10, v11
	v_mfma_f32_32x32x16_bf16 v[48:63], v[72:75], v[216:219], v[48:63]
	v_cvt_pk_bf16_f32 v220, v40, v41
	v_cvt_pk_bf16_f32 v221, v42, v43
	v_cvt_pk_bf16_f32 v222, v44, v45
	v_cvt_pk_bf16_f32 v223, v46, v47
	v_add_f32_e32 v2, v2, v0
	v_add_f32_e32 v3, v3, v14
	v_mfma_f32_32x32x16_bf16 v[48:63], v[76:79], v[220:223], v[48:63]
	s_nop 11
	v_cvt_pk_bf16_f32 v232, v48, v108
	v_fma_f32 v13, v48, v2, v49
	v_fma_f32 v13, v108, v3, v13
	v_mfma_f32_32x32x16_bf16 v[16:31], v[224:227], v[232:235], v[16:31]
	v_mfma_f32_32x32x16_bf16 v[32:47], v[228:231], v[232:235], v[32:47]
	ds_write_b32 v191, v13 offset:2048
	s_waitcnt lgkmcnt(1)
; DI unsigned cvtpk_n(float lo, float hi) { f32x2 v = {lo, hi}; bf16x2n b = __builtin_convertvector(v, bf16x2n); return __builtin_bit_cast(unsigned, b); }
; DI void phase_scan(const bf16_t* R, const bf16_t* Kk, const bf16_t* V, const __half* DEC, const bf16_t* AA, const float* INV, const float* kkp, const float* kap,
;                    bf16_t* MIX, bf16_t* YB, char* lds) {
;     ...
;                 for (int st = 0; st < 16; ++st) {
;                     f32x16 d0 = __builtin_amdgcn_mfma_f32_32x32x16_bf16(t.f[0], pack_acc(acc0, 0), zero16, 0, 0, 0);
;                     d0 = __builtin_amdgcn_mfma_f32_32x32x16_bf16(t.f[1], pack_acc(acc0, 1), d0, 0, 0, 0);
;                     d0 = __builtin_amdgcn_mfma_f32_32x32x16_bf16(t.f[2], pack_acc(acc1, 0), d0, 0, 0, 0);
;                     d0 = __builtin_amdgcn_mfma_f32_32x32x16_bf16(t.f[3], pack_acc(acc1, 1), d0, 0, 0, 0);
;                     __builtin_amdgcn_sched_barrier(0);
;                     ScanStep n; scan_ld(n, cur + (st + 1) * SREC, zimg, fragoff, isaq, h, m, vrow);
;                     __builtin_amdgcn_sched_barrier(0);
;                     const float sa = d0[0], z = d0[1];
;                     yb[st * 64 + vrow] = z + sa * ((t.brp[0] + t.brp[1]) + (t.brp[2] + t.brp[3])) + t.v * ((t.krp[0] + t.krp[1]) + (t.krp[2] + t.krp[3]));
;                     const unsigned hz = h ? 0u : 0xffffffffu;
;                     const u32x4 ua0 = {cvtpk_n(t.b0, t.k0) & hz, 0u, 0u, 0u}, ua1 = {cvtpk_n(t.b1, t.k1) & hz, 0u, 0u, 0u}, ub = {cvtpk_n(sa, t.v) & hz, 0u, 0u, 0u};
;                     acc0 = __builtin_amdgcn_mfma_f32_32x32x16_bf16(__builtin_bit_cast(bf16x8, ua0), __builtin_bit_cast(bf16x8, ub), acc0, 0, 0, 0);
;                     acc1 = __builtin_amdgcn_mfma_f32_32x32x16_bf16(__builtin_bit_cast(bf16x8, ua1), __builtin_bit_cast(bf16x8, ub), acc1, 0, 0, 0);
;                     t = n;
;                 }
	s_mov_b64 exec, s[40:41]
	ds_read_b128 v[64:67], v188 offset:10560
	ds_read_b128 v[68:71], v188 offset:10592
	ds_read_b128 v[72:75], v188 offset:10624
	ds_read_b128 v[76:79], v188 offset:10656
	s_mov_b64 exec, -1
	ds_read_b32 v224, v189 offset:10560
	ds_read_b32 v228, v189 offset:10688
	ds_read_b32 v108, v190 offset:10560
	v_cvt_pk_bf16_f32 v216, v16, v17
	v_cvt_pk_bf16_f32 v217, v18, v19
	v_cvt_pk_bf16_f32 v218, v20, v21
	v_cvt_pk_bf16_f32 v219, v22, v23
	ds_read_b128 v[4:7], v170 offset:11584
	ds_read_b128 v[8:11], v170 offset:11600
	v_mfma_f32_32x32x16_bf16 v[48:63], v[192:195], v[216:219], 0
	v_cvt_pk_bf16_f32 v220, v24, v25
	v_cvt_pk_bf16_f32 v221, v26, v27
	v_cvt_pk_bf16_f32 v222, v28, v29
	v_cvt_pk_bf16_f32 v223, v30, v31
	v_add_f32_e32 v2, v208, v209
	v_add_f32_e32 v3, v212, v213
	v_mfma_f32_32x32x16_bf16 v[48:63], v[196:199], v[220:223], v[48:63]
	v_cvt_pk_bf16_f32 v216, v32, v33
	v_cvt_pk_bf16_f32 v217, v34, v35
	v_cvt_pk_bf16_f32 v218, v36, v37
	v_cvt_pk_bf16_f32 v219, v38, v39
	v_add_f32_e32 v0, v210, v211
	v_add_f32_e32 v14, v214, v215
	v_mfma_f32_32x32x16_bf16 v[48:63], v[200:203], v[216:219], v[48:63]
	v_cvt_pk_bf16_f32 v220, v40, v41
	v_cvt_pk_bf16_f32 v221, v42, v43
	v_cvt_pk_bf16_f32 v222, v44, v45
	v_cvt_pk_bf16_f32 v223, v46, v47
	v_add_f32_e32 v2, v2, v0
	v_add_f32_e32 v3, v3, v14
	v_mfma_f32_32x32x16_bf16 v[48:63], v[204:207], v[220:223], v[48:63]
	s_nop 11
	v_cvt_pk_bf16_f32 v232, v48, v114
	v_fma_f32 v13, v48, v2, v49
	v_fma_f32 v13, v114, v3, v13
	v_mfma_f32_32x32x16_bf16 v[16:31], v[80:83], v[232:235], v[16:31]
	v_mfma_f32_32x32x16_bf16 v[32:47], v[84:87], v[232:235], v[32:47]
	ds_write_b32 v191, v13 offset:2304
	s_waitcnt lgkmcnt(1)
	s_mov_b64 exec, s[40:41]
	ds_read_b128 v[192:195], v188 offset:11616
	ds_read_b128 v[196:199], v188 offset:11648
	ds_read_b128 v[200:203], v188 offset:11680
	ds_read_b128 v[204:207], v188 offset:11712
	s_mov_b64 exec, -1
	ds_read_b32 v80, v189 offset:11616
	ds_read_b32 v84, v189 offset:11744
	ds_read_b32 v114, v190 offset:11616
	v_cvt_pk_bf16_f32 v216, v16, v17
	v_cvt_pk_bf16_f32 v217, v18, v19
	v_cvt_pk_bf16_f32 v218, v20, v21
	v_cvt_pk_bf16_f32 v219, v22, v23
	ds_read_b128 v[208:211], v170 offset:12640
	ds_read_b128 v[212:215], v170 offset:12656
	v_mfma_f32_32x32x16_bf16 v[48:63], v[64:67], v[216:219], 0
	v_cvt_pk_bf16_f32 v220, v24, v25
	v_cvt_pk_bf16_f32 v221, v26, v27
	v_cvt_pk_bf16_f32 v222, v28, v29
	v_cvt_pk_bf16_f32 v223, v30, v31
	v_add_f32_e32 v2, v4, v5
	v_add_f32_e32 v3, v8, v9
	v_mfma_f32_32x32x16_bf16 v[48:63], v[68:71], v[220:223], v[48:63]
	v_cvt_pk_bf16_f32 v216, v32, v33
	v_cvt_pk_bf16_f32 v217, v34, v35
	v_cvt_pk_bf16_f32 v218, v36, v37
	v_cvt_pk_bf16_f32 v219, v38, v39
	v_add_f32_e32 v0, v6, v7
	v_add_f32_e32 v14, v10, v11
	v_mfma_f32_32x32x16_bf16 v[48:63], v[72:75], v[216:219], v[48:63]
	v_cvt_pk_bf16_f32 v220, v40, v41
	v_cvt_pk_bf16_f32 v221, v42, v43
	v_cvt_pk_bf16_f32 v222, v44, v45
	v_cvt_pk_bf16_f32 v223, v46, v47
	v_add_f32_e32 v2, v2, v0
	v_add_f32_e32 v3, v3, v14
	v_mfma_f32_32x32x16_bf16 v[48:63], v[76:79], v[220:223], v[48:63]
	s_nop 11
	v_cvt_pk_bf16_f32 v232, v48, v108
	v_fma_f32 v13, v48, v2, v49
	v_fma_f32 v13, v108, v3, v13
	v_mfma_f32_32x32x16_bf16 v[16:31], v[224:227], v[232:235], v[16:31]
	v_mfma_f32_32x32x16_bf16 v[32:47], v[228:231], v[232:235], v[32:47]
	ds_write_b32 v191, v13 offset:2560
	s_waitcnt lgkmcnt(1)
	s_mov_b64 exec, s[40:41]
	ds_read_b128 v[64:67], v188 offset:12672
	ds_read_b128 v[68:71], v188 offset:12704
	ds_read_b128 v[72:75], v188 offset:12736
	ds_read_b128 v[76:79], v188 offset:12768
	s_mov_b64 exec, -1
	ds_read_b32 v224, v189 offset:12672
	ds_read_b32 v228, v189 offset:12800
	ds_read_b32 v108, v190 offset:12672
	v_cvt_pk_bf16_f32 v216, v16, v17
	v_cvt_pk_bf16_f32 v217, v18, v19
	v_cvt_pk_bf16_f32 v218, v20, v21
	v_cvt_pk_bf16_f32 v219, v22, v23
	ds_read_b128 v[4:7], v170 offset:13696
	ds_read_b128 v[8:11], v170 offset:13712
	v_mfma_f32_32x32x16_bf16 v[48:63], v[192:195], v[216:219], 0
	v_cvt_pk_bf16_f32 v220, v24, v25
	v_cvt_pk_bf16_f32 v221, v26, v27
	v_cvt_pk_bf16_f32 v222, v28, v29
	v_cvt_pk_bf16_f32 v223, v30, v31
	v_add_f32_e32 v2, v208, v209
	v_add_f32_e32 v3, v212, v213
	v_mfma_f32_32x32x16_bf16 v[48:63], v[196:199], v[220:223], v[48:63]
	v_cvt_pk_bf16_f32 v216, v32, v33
	v_cvt_pk_bf16_f32 v217, v34, v35
	v_cvt_pk_bf16_f32 v218, v36, v37
	v_cvt_pk_bf16_f32 v219, v38, v39
	v_add_f32_e32 v0, v210, v211
	v_add_f32_e32 v14, v214, v215
	v_mfma_f32_32x32x16_bf16 v[48:63], v[200:203], v[216:219], v[48:63]
	v_cvt_pk_bf16_f32 v220, v40, v41
	v_cvt_pk_bf16_f32 v221, v42, v43
	v_cvt_pk_bf16_f32 v222, v44, v45
	v_cvt_pk_bf16_f32 v223, v46, v47
	v_add_f32_e32 v2, v2, v0
	v_add_f32_e32 v3, v3, v14
	v_mfma_f32_32x32x16_bf16 v[48:63], v[204:207], v[220:223], v[48:63]
	s_nop 11
	v_cvt_pk_bf16_f32 v232, v48, v114
	v_fma_f32 v13, v48, v2, v49
	v_fma_f32 v13, v114, v3, v13
	v_mfma_f32_32x32x16_bf16 v[16:31], v[80:83], v[232:235], v[16:31]
	v_mfma_f32_32x32x16_bf16 v[32:47], v[84:87], v[232:235], v[32:47]
	ds_write_b32 v191, v13 offset:2816
	s_waitcnt lgkmcnt(1)
; DI unsigned cvtpk_n(float lo, float hi) { f32x2 v = {lo, hi}; bf16x2n b = __builtin_convertvector(v, bf16x2n); return __builtin_bit_cast(unsigned, b); }
; DI void phase_scan(const bf16_t* R, const bf16_t* Kk, const bf16_t* V, const __half* DEC, const bf16_t* AA, const float* INV, const float* kkp, const float* kap,
;                    bf16_t* MIX, bf16_t* YB, char* lds) {
;     ...
;                 for (int st = 0; st < 16; ++st) {
;                     f32x16 d0 = __builtin_amdgcn_mfma_f32_32x32x16_bf16(t.f[0], pack_acc(acc0, 0), zero16, 0, 0, 0);
;                     d0 = __builtin_amdgcn_mfma_f32_32x32x16_bf16(t.f[1], pack_acc(acc0, 1), d0, 0, 0, 0);
;                     d0 = __builtin_amdgcn_mfma_f32_32x32x16_bf16(t.f[2], pack_acc(acc1, 0), d0, 0, 0, 0);
;                     d0 = __builtin_amdgcn_mfma_f32_32x32x16_bf16(t.f[3], pack_acc(acc1, 1), d0, 0, 0, 0);
;                     __builtin_amdgcn_sched_barrier(0);
;                     ScanStep n; scan_ld(n, cur + (st + 1) * SREC, zimg, fragoff, isaq, h, m, vrow);
;                     __builtin_amdgcn_sched_barrier(0);
;                     const float sa = d0[0], z = d0[1];
;                     yb[st * 64 + vrow] = z + sa * ((t.brp[0] + t.brp[1]) + (t.brp[2] + t.brp[3])) + t.v * ((t.krp[0] + t.krp[1]) + (t.krp[2] + t.krp[3]));
;                     const unsigned hz = h ? 0u : 0xffffffffu;
;                     const u32x4 ua0 = {cvtpk_n(t.b0, t.k0) & hz, 0u, 0u, 0u}, ua1 = {cvtpk_n(t.b1, t.k1) & hz, 0u, 0u, 0u}, ub = {cvtpk_n(sa, t.v) & hz, 0u, 0u, 0u};
;                     acc0 = __builtin_amdgcn_mfma_f32_32x32x16_bf16(__builtin_bit_cast(bf16x8, ua0), __builtin_bit_cast(bf16x8, ub), acc0, 0, 0, 0);
;                     acc1 = __builtin_amdgcn_mfma_f32_32x32x16_bf16(__builtin_bit_cast(bf16x8, ua1), __builtin_bit_cast(bf16x8, ub), acc1, 0, 0, 0);
;                     t = n;
;                 }
	s_mov_b64 exec, s[40:41]
	ds_read_b128 v[192:195], v188 offset:13728
	ds_read_b128 v[196:199], v188 offset:13760
	ds_read_b128 v[200:203], v188 offset:13792
	ds_read_b128 v[204:207], v188 offset:13824
	s_mov_b64 exec, -1
	ds_read_b32 v80, v189 offset:13728
	ds_read_b32 v84, v189 offset:13856
	ds_read_b32 v114, v190 offset:13728
	v_cvt_pk_bf16_f32 v216, v16, v17
	v_cvt_pk_bf16_f32 v217, v18, v19
	v_cvt_pk_bf16_f32 v218, v20, v21
	v_cvt_pk_bf16_f32 v219, v22, v23
	ds_read_b128 v[208:211], v170 offset:14752
	ds_read_b128 v[212:215], v170 offset:14768
	v_mfma_f32_32x32x16_bf16 v[48:63], v[64:67], v[216:219], 0
	v_cvt_pk_bf16_f32 v220, v24, v25
	v_cvt_pk_bf16_f32 v221, v26, v27
	v_cvt_pk_bf16_f32 v222, v28, v29
	v_cvt_pk_bf16_f32 v223, v30, v31
	v_add_f32_e32 v2, v4, v5
	v_add_f32_e32 v3, v8, v9
	v_mfma_f32_32x32x16_bf16 v[48:63], v[68:71], v[220:223], v[48:63]
	v_cvt_pk_bf16_f32 v216, v32, v33
	v_cvt_pk_bf16_f32 v217, v34, v35
	v_cvt_pk_bf16_f32 v218, v36, v37
	v_cvt_pk_bf16_f32 v219, v38, v39
	v_add_f32_e32 v0, v6, v7
	v_add_f32_e32 v14, v10, v11
	v_mfma_f32_32x32x16_bf16 v[48:63], v[72:75], v[216:219], v[48:63]
	v_cvt_pk_bf16_f32 v220, v40, v41
	v_cvt_pk_bf16_f32 v221, v42, v43
	v_cvt_pk_bf16_f32 v222, v44, v45
	v_cvt_pk_bf16_f32 v223, v46, v47
	v_add_f32_e32 v2, v2, v0
	v_add_f32_e32 v3, v3, v14
	v_mfma_f32_32x32x16_bf16 v[48:63], v[76:79], v[220:223], v[48:63]
	s_nop 11
	v_cvt_pk_bf16_f32 v232, v48, v108
	v_fma_f32 v13, v48, v2, v49
	v_fma_f32 v13, v108, v3, v13
	v_mfma_f32_32x32x16_bf16 v[16:31], v[224:227], v[232:235], v[16:31]
	v_mfma_f32_32x32x16_bf16 v[32:47], v[228:231], v[232:235], v[32:47]
	ds_write_b32 v191, v13 offset:3072
	s_waitcnt lgkmcnt(1)
	s_mov_b64 exec, s[40:41]
	ds_read_b128 v[64:67], v188 offset:14784
	ds_read_b128 v[68:71], v188 offset:14816
	ds_read_b128 v[72:75], v188 offset:14848
	ds_read_b128 v[76:79], v188 offset:14880
	s_mov_b64 exec, -1
	ds_read_b32 v224, v189 offset:14784
	ds_read_b32 v228, v189 offset:14912
	ds_read_b32 v108, v190 offset:14784
	v_cvt_pk_bf16_f32 v216, v16, v17
	v_cvt_pk_bf16_f32 v217, v18, v19
	v_cvt_pk_bf16_f32 v218, v20, v21
	v_cvt_pk_bf16_f32 v219, v22, v23
	ds_read_b128 v[4:7], v170 offset:15808
	ds_read_b128 v[8:11], v170 offset:15824
	v_mfma_f32_32x32x16_bf16 v[48:63], v[192:195], v[216:219], 0
	v_cvt_pk_bf16_f32 v220, v24, v25
	v_cvt_pk_bf16_f32 v221, v26, v27
	v_cvt_pk_bf16_f32 v222, v28, v29
	v_cvt_pk_bf16_f32 v223, v30, v31
	v_add_f32_e32 v2, v208, v209
	v_add_f32_e32 v3, v212, v213
	v_mfma_f32_32x32x16_bf16 v[48:63], v[196:199], v[220:223], v[48:63]
	v_cvt_pk_bf16_f32 v216, v32, v33
	v_cvt_pk_bf16_f32 v217, v34, v35
	v_cvt_pk_bf16_f32 v218, v36, v37
	v_cvt_pk_bf16_f32 v219, v38, v39
	v_add_f32_e32 v0, v210, v211
	v_add_f32_e32 v14, v214, v215
	v_mfma_f32_32x32x16_bf16 v[48:63], v[200:203], v[216:219], v[48:63]
	v_cvt_pk_bf16_f32 v220, v40, v41
	v_cvt_pk_bf16_f32 v221, v42, v43
	v_cvt_pk_bf16_f32 v222, v44, v45
	v_cvt_pk_bf16_f32 v223, v46, v47
	v_add_f32_e32 v2, v2, v0
	v_add_f32_e32 v3, v3, v14
	v_mfma_f32_32x32x16_bf16 v[48:63], v[204:207], v[220:223], v[48:63]
	s_nop 11
	v_cvt_pk_bf16_f32 v232, v48, v114
	v_fma_f32 v13, v48, v2, v49
	v_fma_f32 v13, v114, v3, v13
	v_mfma_f32_32x32x16_bf16 v[16:31], v[80:83], v[232:235], v[16:31]
	v_mfma_f32_32x32x16_bf16 v[32:47], v[84:87], v[232:235], v[32:47]
	ds_write_b32 v191, v13 offset:3328
	s_waitcnt lgkmcnt(1)
	s_mov_b64 exec, s[40:41]
	ds_read_b128 v[192:195], v188 offset:15840
	ds_read_b128 v[196:199], v188 offset:15872
	ds_read_b128 v[200:203], v188 offset:15904
	ds_read_b128 v[204:207], v188 offset:15936
	s_mov_b64 exec, -1
	ds_read_b32 v80, v189 offset:15840
	ds_read_b32 v84, v189 offset:15968
	ds_read_b32 v114, v190 offset:15840
	v_cvt_pk_bf16_f32 v216, v16, v17
	v_cvt_pk_bf16_f32 v217, v18, v19
	v_cvt_pk_bf16_f32 v218, v20, v21
	v_cvt_pk_bf16_f32 v219, v22, v23
	ds_read_b128 v[208:211], v170 offset:16864
	ds_read_b128 v[212:215], v170 offset:16880
	v_mfma_f32_32x32x16_bf16 v[48:63], v[64:67], v[216:219], 0
	v_cvt_pk_bf16_f32 v220, v24, v25
	v_cvt_pk_bf16_f32 v221, v26, v27
	v_cvt_pk_bf16_f32 v222, v28, v29
	v_cvt_pk_bf16_f32 v223, v30, v31
	v_add_f32_e32 v2, v4, v5
	v_add_f32_e32 v3, v8, v9
	v_mfma_f32_32x32x16_bf16 v[48:63], v[68:71], v[220:223], v[48:63]
	v_cvt_pk_bf16_f32 v216, v32, v33
	v_cvt_pk_bf16_f32 v217, v34, v35
	v_cvt_pk_bf16_f32 v218, v36, v37
	v_cvt_pk_bf16_f32 v219, v38, v39
	v_add_f32_e32 v0, v6, v7
	v_add_f32_e32 v14, v10, v11
	v_mfma_f32_32x32x16_bf16 v[48:63], v[72:75], v[216:219], v[48:63]
	v_cvt_pk_bf16_f32 v220, v40, v41
	v_cvt_pk_bf16_f32 v221, v42, v43
	v_cvt_pk_bf16_f32 v222, v44, v45
	v_cvt_pk_bf16_f32 v223, v46, v47
	v_add_f32_e32 v2, v2, v0
	v_add_f32_e32 v3, v3, v14
	v_mfma_f32_32x32x16_bf16 v[48:63], v[76:79], v[220:223], v[48:63]
	s_nop 11
	v_cvt_pk_bf16_f32 v232, v48, v108
	v_fma_f32 v13, v48, v2, v49
	v_fma_f32 v13, v108, v3, v13
	v_mfma_f32_32x32x16_bf16 v[16:31], v[224:227], v[232:235], v[16:31]
	v_mfma_f32_32x32x16_bf16 v[32:47], v[228:231], v[232:235], v[32:47]
	ds_write_b32 v191, v13 offset:3584
	s_waitcnt lgkmcnt(1)
; DI unsigned cvtpk_n(float lo, float hi) { f32x2 v = {lo, hi}; bf16x2n b = __builtin_convertvector(v, bf16x2n); return __builtin_bit_cast(unsigned, b); }
; DI void phase_scan(const bf16_t* R, const bf16_t* Kk, const bf16_t* V, const __half* DEC, const bf16_t* AA, const float* INV, const float* kkp, const float* kap,
;                    bf16_t* MIX, bf16_t* YB, char* lds) {
;     ...
;                 for (int st = 0; st < 16; ++st) {
;                     f32x16 d0 = __builtin_amdgcn_mfma_f32_32x32x16_bf16(t.f[0], pack_acc(acc0, 0), zero16, 0, 0, 0);
;                     d0 = __builtin_amdgcn_mfma_f32_32x32x16_bf16(t.f[1], pack_acc(acc0, 1), d0, 0, 0, 0);
;                     d0 = __builtin_amdgcn_mfma_f32_32x32x16_bf16(t.f[2], pack_acc(acc1, 0), d0, 0, 0, 0);
;                     d0 = __builtin_amdgcn_mfma_f32_32x32x16_bf16(t.f[3], pack_acc(acc1, 1), d0, 0, 0, 0);
;                     __builtin_amdgcn_sched_barrier(0);
;                     ScanStep n; scan_ld(n, cur + (st + 1) * SREC, zimg, fragoff, isaq, h, m, vrow);
;                     __builtin_amdgcn_sched_barrier(0);
;                     const float sa = d0[0], z = d0[1];
;                     yb[st * 64 + vrow] = z + sa * ((t.brp[0] + t.brp[1]) + (t.brp[2] + t.brp[3])) + t.v * ((t.krp[0] + t.krp[1]) + (t.krp[2] + t.krp[3]));
;                     const unsigned hz = h ? 0u : 0xffffffffu;
;                     const u32x4 ua0 = {cvtpk_n(t.b0, t.k0) & hz, 0u, 0u, 0u}, ua1 = {cvtpk_n(t.b1, t.k1) & hz, 0u, 0u, 0u}, ub = {cvtpk_n(sa, t.v) & hz, 0u, 0u, 0u};
;                     acc0 = __builtin_amdgcn_mfma_f32_32x32x16_bf16(__builtin_bit_cast(bf16x8, ua0), __builtin_bit_cast(bf16x8, ub), acc0, 0, 0, 0);
;                     acc1 = __builtin_amdgcn_mfma_f32_32x32x16_bf16(__builtin_bit_cast(bf16x8, ua1), __builtin_bit_cast(bf16x8, ub), acc1, 0, 0, 0);
;                     t = n;
;                 }
;                 const float* wc = cur + 16 * SREC;
; #pragma unroll
;                 for (int g_ = 0; g_ < 4; ++g_) { const f32x4 w0 = *(const f32x4*)(wc + 8 * g_ + 4 * h), w1 = *(const f32x4*)(wc + 32 + 8 * g_ + 4 * h);
; #pragma unroll
;                     for (int e = 0; e < 4; ++e) { acc0[4 * g_ + e] *= w0[e]; acc1[4 * g_ + e] *= w1[e]; } }
	s_nop 8
	v_cvt_pk_bf16_f32 v216, v16, v17
	v_cvt_pk_bf16_f32 v217, v18, v19
	v_cvt_pk_bf16_f32 v218, v20, v21
	v_cvt_pk_bf16_f32 v219, v22, v23
	s_nop 1
	v_mfma_f32_32x32x16_bf16 v[48:63], v[192:195], v[216:219], 0
	v_cvt_pk_bf16_f32 v220, v24, v25
	v_cvt_pk_bf16_f32 v221, v26, v27
	v_cvt_pk_bf16_f32 v222, v28, v29
	v_cvt_pk_bf16_f32 v223, v30, v31
	v_add_f32_e32 v2, v208, v209
	v_add_f32_e32 v3, v212, v213
	v_mfma_f32_32x32x16_bf16 v[48:63], v[196:199], v[220:223], v[48:63]
	v_cvt_pk_bf16_f32 v216, v32, v33
	v_cvt_pk_bf16_f32 v217, v34, v35
	v_cvt_pk_bf16_f32 v218, v36, v37
	v_cvt_pk_bf16_f32 v219, v38, v39
	v_add_f32_e32 v0, v210, v211
	v_add_f32_e32 v14, v214, v215
	v_mfma_f32_32x32x16_bf16 v[48:63], v[200:203], v[216:219], v[48:63]
	v_cvt_pk_bf16_f32 v220, v40, v41
	v_cvt_pk_bf16_f32 v221, v42, v43
	v_cvt_pk_bf16_f32 v222, v44, v45
	v_cvt_pk_bf16_f32 v223, v46, v47
	v_add_f32_e32 v2, v2, v0
	v_add_f32_e32 v3, v3, v14
	v_mfma_f32_32x32x16_bf16 v[48:63], v[204:207], v[220:223], v[48:63]
	s_nop 11
	v_cvt_pk_bf16_f32 v232, v48, v114
	v_fma_f32 v13, v48, v2, v49
	v_fma_f32 v13, v114, v3, v13
	v_mfma_f32_32x32x16_bf16 v[16:31], v[80:83], v[232:235], v[16:31]
	v_mfma_f32_32x32x16_bf16 v[32:47], v[84:87], v[232:235], v[32:47]
	ds_write_b32 v191, v13 offset:3840
	v_lshl_add_u32 v0, v136, 2, v170
	ds_read_b128 v[2:5], v0 offset:16896
	ds_read_b128 v[6:9], v0 offset:16928
	s_waitcnt lgkmcnt(0)
	ds_read_b128 v[10:13], v0 offset:16960
	ds_read_b128 v[48:51], v0 offset:16992
	ds_read_b128 v[52:55], v0 offset:17024
	ds_read_b128 v[56:59], v0 offset:17056
	ds_read_b128 v[60:63], v0 offset:17088
	ds_read_b128 v[88:91], v0 offset:17120
	s_waitcnt lgkmcnt(0)
	v_pk_mul_f32 v[30:31], v[30:31], v[50:51]
	v_pk_mul_f32 v[26:27], v[26:27], v[12:13]
	v_pk_mul_f32 v[22:23], v[22:23], v[8:9]
	v_pk_mul_f32 v[18:19], v[18:19], v[4:5]
	v_pk_mul_f32 v[28:29], v[28:29], v[48:49]
	v_pk_mul_f32 v[24:25], v[24:25], v[10:11]
	v_pk_mul_f32 v[20:21], v[20:21], v[6:7]
	v_pk_mul_f32 v[16:17], v[16:17], v[2:3]
	v_pk_mul_f32 v[46:47], v[46:47], v[90:91]
	v_pk_mul_f32 v[42:43], v[42:43], v[62:63]
	v_pk_mul_f32 v[38:39], v[38:39], v[58:59]
	v_pk_mul_f32 v[34:35], v[34:35], v[54:55]
	v_pk_mul_f32 v[44:45], v[44:45], v[88:89]
	v_pk_mul_f32 v[40:41], v[40:41], v[60:61]
	v_pk_mul_f32 v[36:37], v[36:37], v[56:57]
	v_pk_mul_f32 v[32:33], v[32:33], v[52:53]
	s_branch .LBB0_2281
	s_nop 0
	s_nop 0
	s_nop 0
	s_nop 0
	s_nop 0
	s_nop 0
	s_nop 0
	s_nop 0
	s_nop 0
	s_nop 0
	s_nop 0
	s_nop 0
	s_nop 0
	s_nop 0
	s_nop 0
	s_nop 0
	s_nop 0
	s_nop 0
	s_nop 0
	s_nop 0
	s_nop 0
	s_nop 0
	s_nop 0
	s_nop 0
	s_nop 0
	s_nop 0
	s_nop 0
	s_nop 0
	s_nop 0
	s_nop 0
	s_nop 0
	s_nop 0
	s_nop 0
	s_nop 0
	s_nop 0
	s_nop 0
	s_nop 0
	s_nop 0
	s_nop 0
	s_nop 0
	s_nop 0
	s_nop 0
	s_nop 0
	s_nop 0
	s_nop 0
	s_nop 0
	s_nop 0
	s_nop 0
	s_nop 0
	s_nop 0
	s_nop 0
	s_nop 0
	s_nop 0
	s_nop 0
	s_nop 0
	s_nop 0
	s_nop 0
	s_nop 0
	s_nop 0
	s_nop 0
	s_nop 0
	s_nop 0
	s_nop 0
	s_nop 0
	s_nop 0
	s_nop 0
	s_nop 0
	s_nop 0
	s_nop 0
	s_nop 0
	s_nop 0
	s_nop 0
	s_nop 0
	s_nop 0
	s_nop 0
	s_nop 0
	s_nop 0
	s_nop 0
	s_nop 0
	s_nop 0
	s_nop 0
	s_nop 0
	s_nop 0
	s_nop 0
	s_nop 0
	s_nop 0
	s_nop 0
	s_nop 0
	s_nop 0
	s_nop 0
	s_nop 0
	s_nop 0
	s_nop 0
	s_nop 0
	s_nop 0
	s_nop 0
	s_nop 0
	s_nop 0
	s_nop 0
	s_nop 0
	s_nop 0
	s_nop 0
	s_nop 0
	s_nop 0
	s_nop 0
	s_nop 0
	s_nop 0
	s_nop 0
	s_nop 0
	s_nop 0
	s_nop 0
	s_nop 0
	s_nop 0
	s_nop 0
	s_nop 0
	s_nop 0
	s_nop 0
	s_nop 0
	s_nop 0
	s_nop 0
	s_nop 0
	s_nop 0
	s_nop 0
	s_nop 0
	s_nop 0
	s_nop 0
	s_nop 0
	s_nop 0
